# main GEMM K-loop: LDS-DMA loads use scalar-base + 32-bit lane offset form (no 64-bit VALU address add per DMA; t+3 tiles via offset:128 with M0-128)
# speedup vs baseline: 1.0068x; 1.0068x over previous
.LBB0_246:
	s_add_i32 s90, s42, 2
	s_add_u32 s91, s6, 0x80
	s_addc_u32 s43, s7, 0
	s_add_i32 s94, 0, 0x10000
	s_cmp_eq_u32 s72, s42
	s_cselect_b32 s43, s89, s43
	s_cselect_b32 s42, s88, s91
	s_cselect_b32 s93, s1, s66
	s_cselect_b32 s92, s0, s8
	s_add_i32 s91, 0, 0x14000
	v_add_u32_e32 v140, s94, v157
	v_add_u32_e32 v144, s91, v157
	ds_read_b128 v[128:131], v140
	ds_read_b128 v[132:135], v140 offset:1024
	ds_read_b128 v[136:139], v140 offset:2048
	ds_read_b128 v[140:143], v140 offset:3072
	ds_read_b128 v[168:171], v144
	ds_read_b128 v[172:175], v144 offset:1024
	ds_read_b128 v[176:179], v144 offset:2048
	ds_read_b128 v[180:183], v144 offset:3072
	s_add_i32 m0, s68, 0xc000
	ds_read_b128 v[190:193], v188
	ds_read_b128 v[194:197], v188 offset:1024
	ds_read_b128 v[198:201], v188 offset:2048
	ds_read_b128 v[202:205], v188 offset:3072
	ds_read_b128 v[206:209], v188 offset:4096
	ds_read_b128 v[210:213], v188 offset:5120
	ds_read_b128 v[214:217], v188 offset:6144
	ds_read_b128 v[218:221], v188 offset:7168
	global_load_lds_dwordx4 v162, s[6:7]
	s_add_i32 m0, s68, 0xe000
	s_nop 0
	global_load_lds_dwordx4 v164, s[6:7]
	s_waitcnt vmcnt(8)
	s_waitcnt lgkmcnt(0)
	s_barrier
	s_setprio 1
	s_waitcnt lgkmcnt(0)
	v_mfma_f32_16x16x32_bf16 v[124:127], v[128:131], v[190:193], v[124:127]
	v_mfma_f32_16x16x32_bf16 v[120:123], v[136:139], v[190:193], v[120:123]
	v_mfma_f32_16x16x32_bf16 v[116:119], v[128:131], v[198:201], v[116:119]
	v_mfma_f32_16x16x32_bf16 v[112:115], v[136:139], v[198:201], v[112:115]
	v_mfma_f32_16x16x32_bf16 v[100:103], v[128:131], v[206:209], v[100:103]
	v_mfma_f32_16x16x32_bf16 v[96:99], v[136:139], v[206:209], v[96:99]
	v_mfma_f32_16x16x32_bf16 v[84:87], v[128:131], v[214:217], v[84:87]
	v_mfma_f32_16x16x32_bf16 v[80:83], v[136:139], v[214:217], v[80:83]
	v_mfma_f32_16x16x32_bf16 v[124:127], v[132:135], v[194:197], v[124:127]
	v_mfma_f32_16x16x32_bf16 v[120:123], v[140:143], v[194:197], v[120:123]
	v_mfma_f32_16x16x32_bf16 v[116:119], v[132:135], v[202:205], v[116:119]
	v_mfma_f32_16x16x32_bf16 v[112:115], v[140:143], v[202:205], v[112:115]
	v_mfma_f32_16x16x32_bf16 v[100:103], v[132:135], v[210:213], v[100:103]
	v_mfma_f32_16x16x32_bf16 v[96:99], v[140:143], v[210:213], v[96:99]
	v_mfma_f32_16x16x32_bf16 v[84:87], v[132:135], v[218:221], v[84:87]
	v_mfma_f32_16x16x32_bf16 v[80:83], v[140:143], v[218:221], v[80:83]
	s_setprio 0
	s_setprio 1
	v_mfma_f32_16x16x32_bf16 v[108:111], v[168:171], v[190:193], v[108:111]
	v_mfma_f32_16x16x32_bf16 v[104:107], v[176:179], v[190:193], v[104:107]
	v_mfma_f32_16x16x32_bf16 v[92:95], v[168:171], v[198:201], v[92:95]
	v_mfma_f32_16x16x32_bf16 v[88:91], v[176:179], v[198:201], v[88:91]
	v_mfma_f32_16x16x32_bf16 v[76:79], v[168:171], v[206:209], v[76:79]
	v_mfma_f32_16x16x32_bf16 v[72:75], v[176:179], v[206:209], v[72:75]
	v_mfma_f32_16x16x32_bf16 v[68:71], v[168:171], v[214:217], v[68:71]
	v_mfma_f32_16x16x32_bf16 v[64:67], v[176:179], v[214:217], v[64:67]
	v_mfma_f32_16x16x32_bf16 v[108:111], v[172:175], v[194:197], v[108:111]
	v_mfma_f32_16x16x32_bf16 v[104:107], v[180:183], v[194:197], v[104:107]
	v_mfma_f32_16x16x32_bf16 v[92:95], v[172:175], v[202:205], v[92:95]
	v_mfma_f32_16x16x32_bf16 v[88:91], v[180:183], v[202:205], v[88:91]
	v_mfma_f32_16x16x32_bf16 v[76:79], v[172:175], v[210:213], v[76:79]
	v_mfma_f32_16x16x32_bf16 v[72:75], v[180:183], v[210:213], v[72:75]
	v_mfma_f32_16x16x32_bf16 v[68:71], v[172:175], v[218:221], v[68:71]
	v_mfma_f32_16x16x32_bf16 v[64:67], v[180:183], v[218:221], v[64:67]
	s_setprio 0
	s_barrier
	s_add_i32 s94, s94, s15
	s_mov_b32 m0, s94
	ds_read_b128 v[190:193], v188 offset:16384
	ds_read_b128 v[194:197], v188 offset:17408
	ds_read_b128 v[198:201], v188 offset:18432
	ds_read_b128 v[202:205], v188 offset:19456
	ds_read_b128 v[206:209], v188 offset:20480
	ds_read_b128 v[210:213], v188 offset:21504
	ds_read_b128 v[214:217], v188 offset:22528
	ds_read_b128 v[218:221], v188 offset:23552
	global_load_lds_dwordx4 v148, s[92:93]
	s_add_i32 m0, s94, 0x2000
	s_add_i32 s91, s91, s15
	global_load_lds_dwordx4 v152, s[92:93]
	s_add_u32 s92, s92, s21
	s_addc_u32 s93, s93, 0
	s_mov_b32 m0, s91
	s_nop 0
	global_load_lds_dwordx4 v148, s[92:93]
	s_add_i32 m0, s91, 0x2000
	s_nop 0
	global_load_lds_dwordx4 v152, s[92:93]
	s_mov_b32 m0, s68
	s_nop 0
	global_load_lds_dwordx4 v146, s[42:43]
	s_mov_b32 m0, s23
	s_nop 0
	global_load_lds_dwordx4 v150, s[42:43]
	s_waitcnt vmcnt(8)
	s_waitcnt lgkmcnt(0)
	s_barrier
	s_setprio 1
	s_waitcnt lgkmcnt(0)
	v_mfma_f32_16x16x32_bf16 v[60:63], v[128:131], v[190:193], v[60:63]
	v_mfma_f32_16x16x32_bf16 v[56:59], v[136:139], v[190:193], v[56:59]
	v_mfma_f32_16x16x32_bf16 v[52:55], v[128:131], v[198:201], v[52:55]
	v_mfma_f32_16x16x32_bf16 v[48:51], v[136:139], v[198:201], v[48:51]
	v_mfma_f32_16x16x32_bf16 v[36:39], v[128:131], v[206:209], v[36:39]
	v_mfma_f32_16x16x32_bf16 v[32:35], v[136:139], v[206:209], v[32:35]
	v_mfma_f32_16x16x32_bf16 v[20:23], v[128:131], v[214:217], v[20:23]
	v_mfma_f32_16x16x32_bf16 v[16:19], v[136:139], v[214:217], v[16:19]
	v_mfma_f32_16x16x32_bf16 v[60:63], v[132:135], v[194:197], v[60:63]
	v_mfma_f32_16x16x32_bf16 v[56:59], v[140:143], v[194:197], v[56:59]
	v_mfma_f32_16x16x32_bf16 v[52:55], v[132:135], v[202:205], v[52:55]
	v_mfma_f32_16x16x32_bf16 v[48:51], v[140:143], v[202:205], v[48:51]
	v_mfma_f32_16x16x32_bf16 v[36:39], v[132:135], v[210:213], v[36:39]
	v_mfma_f32_16x16x32_bf16 v[32:35], v[140:143], v[210:213], v[32:35]
	v_mfma_f32_16x16x32_bf16 v[20:23], v[132:135], v[218:221], v[20:23]
	v_mfma_f32_16x16x32_bf16 v[16:19], v[140:143], v[218:221], v[16:19]
	s_setprio 0
	s_setprio 1
	v_mfma_f32_16x16x32_bf16 v[44:47], v[168:171], v[190:193], v[44:47]
	v_mfma_f32_16x16x32_bf16 v[40:43], v[176:179], v[190:193], v[40:43]
	v_mfma_f32_16x16x32_bf16 v[28:31], v[168:171], v[198:201], v[28:31]
	v_mfma_f32_16x16x32_bf16 v[24:27], v[176:179], v[198:201], v[24:27]
	v_mfma_f32_16x16x32_bf16 v[12:15], v[168:171], v[206:209], v[12:15]
	v_mfma_f32_16x16x32_bf16 v[8:11], v[176:179], v[206:209], v[8:11]
	v_mfma_f32_16x16x32_bf16 v[4:7], v[168:171], v[214:217], v[4:7]
	v_mfma_f32_16x16x32_bf16 v[0:3], v[176:179], v[214:217], v[0:3]
	v_mfma_f32_16x16x32_bf16 v[44:47], v[172:175], v[194:197], v[44:47]
	v_mfma_f32_16x16x32_bf16 v[40:43], v[180:183], v[194:197], v[40:43]
	v_mfma_f32_16x16x32_bf16 v[28:31], v[172:175], v[202:205], v[28:31]
	v_mfma_f32_16x16x32_bf16 v[24:27], v[180:183], v[202:205], v[24:27]
	v_mfma_f32_16x16x32_bf16 v[12:15], v[172:175], v[210:213], v[12:15]
	v_mfma_f32_16x16x32_bf16 v[8:11], v[180:183], v[210:213], v[8:11]
	v_mfma_f32_16x16x32_bf16 v[4:7], v[172:175], v[218:221], v[4:7]
	v_mfma_f32_16x16x32_bf16 v[0:3], v[180:183], v[218:221], v[0:3]
	s_setprio 0
	s_barrier
	s_add_i32 s91, 0, 0x18000
	s_add_i32 s94, 0, 0x1c000
	v_add_u32_e32 v140, s91, v157
	v_add_u32_e32 v144, s94, v157
	ds_read_b128 v[128:131], v140
	ds_read_b128 v[132:135], v140 offset:1024
	ds_read_b128 v[136:139], v140 offset:2048
	ds_read_b128 v[140:143], v140 offset:3072
	ds_read_b128 v[168:171], v144
	ds_read_b128 v[172:175], v144 offset:1024
	ds_read_b128 v[176:179], v144 offset:2048
	ds_read_b128 v[180:183], v144 offset:3072
	s_add_u32 s42, s42, s48
	s_addc_u32 s43, s43, 0
	s_mov_b32 m0, s40
	ds_read_b128 v[190:193], v188 offset:32768
	ds_read_b128 v[194:197], v188 offset:33792
	ds_read_b128 v[198:201], v188 offset:34816
	ds_read_b128 v[202:205], v188 offset:35840
	ds_read_b128 v[206:209], v188 offset:36864
	ds_read_b128 v[210:213], v188 offset:37888
	ds_read_b128 v[214:217], v188 offset:38912
	ds_read_b128 v[218:221], v188 offset:39936
	global_load_lds_dwordx4 v146, s[42:43]
	s_mov_b32 m0, s41
	s_nop 0
	global_load_lds_dwordx4 v150, s[42:43]
	s_waitcnt vmcnt(8)
	s_waitcnt lgkmcnt(0)
	s_barrier
	s_setprio 1
	s_waitcnt lgkmcnt(0)
	v_mfma_f32_16x16x32_bf16 v[124:127], v[128:131], v[190:193], v[124:127]
	v_mfma_f32_16x16x32_bf16 v[120:123], v[136:139], v[190:193], v[120:123]
	v_mfma_f32_16x16x32_bf16 v[116:119], v[128:131], v[198:201], v[116:119]
	v_mfma_f32_16x16x32_bf16 v[112:115], v[136:139], v[198:201], v[112:115]
	v_mfma_f32_16x16x32_bf16 v[100:103], v[128:131], v[206:209], v[100:103]
	v_mfma_f32_16x16x32_bf16 v[96:99], v[136:139], v[206:209], v[96:99]
	v_mfma_f32_16x16x32_bf16 v[84:87], v[128:131], v[214:217], v[84:87]
	v_mfma_f32_16x16x32_bf16 v[80:83], v[136:139], v[214:217], v[80:83]
	v_mfma_f32_16x16x32_bf16 v[124:127], v[132:135], v[194:197], v[124:127]
	v_mfma_f32_16x16x32_bf16 v[120:123], v[140:143], v[194:197], v[120:123]
	v_mfma_f32_16x16x32_bf16 v[116:119], v[132:135], v[202:205], v[116:119]
	v_mfma_f32_16x16x32_bf16 v[112:115], v[140:143], v[202:205], v[112:115]
	v_mfma_f32_16x16x32_bf16 v[100:103], v[132:135], v[210:213], v[100:103]
	v_mfma_f32_16x16x32_bf16 v[96:99], v[140:143], v[210:213], v[96:99]
	v_mfma_f32_16x16x32_bf16 v[84:87], v[132:135], v[218:221], v[84:87]
	v_mfma_f32_16x16x32_bf16 v[80:83], v[140:143], v[218:221], v[80:83]
	s_setprio 0
	s_setprio 1
	v_mfma_f32_16x16x32_bf16 v[108:111], v[168:171], v[190:193], v[108:111]
	v_mfma_f32_16x16x32_bf16 v[104:107], v[176:179], v[190:193], v[104:107]
	v_mfma_f32_16x16x32_bf16 v[92:95], v[168:171], v[198:201], v[92:95]
	v_mfma_f32_16x16x32_bf16 v[88:91], v[176:179], v[198:201], v[88:91]
	v_mfma_f32_16x16x32_bf16 v[76:79], v[168:171], v[206:209], v[76:79]
	v_mfma_f32_16x16x32_bf16 v[72:75], v[176:179], v[206:209], v[72:75]
	v_mfma_f32_16x16x32_bf16 v[68:71], v[168:171], v[214:217], v[68:71]
	v_mfma_f32_16x16x32_bf16 v[64:67], v[176:179], v[214:217], v[64:67]
	v_mfma_f32_16x16x32_bf16 v[108:111], v[172:175], v[194:197], v[108:111]
	v_mfma_f32_16x16x32_bf16 v[104:107], v[180:183], v[194:197], v[104:107]
	v_mfma_f32_16x16x32_bf16 v[92:95], v[172:175], v[202:205], v[92:95]
	v_mfma_f32_16x16x32_bf16 v[88:91], v[180:183], v[202:205], v[88:91]
	v_mfma_f32_16x16x32_bf16 v[76:79], v[172:175], v[210:213], v[76:79]
	v_mfma_f32_16x16x32_bf16 v[72:75], v[180:183], v[210:213], v[72:75]
	v_mfma_f32_16x16x32_bf16 v[68:71], v[172:175], v[218:221], v[68:71]
	v_mfma_f32_16x16x32_bf16 v[64:67], v[180:183], v[218:221], v[64:67]
	s_setprio 0
	s_barrier
	s_add_i32 s91, s91, s15
	s_sub_u32 s92, s92, s21
	s_subb_u32 s93, s93, 0
	s_add_i32 m0, s91, 0xffffff80
	ds_read_b128 v[190:193], v188 offset:49152
	ds_read_b128 v[194:197], v188 offset:50176
	ds_read_b128 v[198:201], v188 offset:51200
	ds_read_b128 v[202:205], v188 offset:52224
	ds_read_b128 v[206:209], v188 offset:53248
	ds_read_b128 v[210:213], v188 offset:54272
	ds_read_b128 v[214:217], v188 offset:55296
	ds_read_b128 v[218:221], v188 offset:56320
	global_load_lds_dwordx4 v148, s[92:93] offset:128
	s_add_i32 m0, s91, 0x1f80
	s_add_i32 s94, s94, s15
	global_load_lds_dwordx4 v152, s[92:93] offset:128
	s_add_u32 s92, s92, s21
	s_addc_u32 s93, s93, 0
	s_add_i32 m0, s94, 0xffffff80
	s_nop 0
	global_load_lds_dwordx4 v148, s[92:93] offset:128
	s_add_i32 m0, s94, 0x1f80
	s_sub_u32 s42, s42, s48
	s_subb_u32 s43, s43, 0
	global_load_lds_dwordx4 v152, s[92:93] offset:128
	s_add_i32 m0, s64, 0xffffff80
	s_nop 0
	global_load_lds_dwordx4 v146, s[42:43] offset:128
	s_add_i32 m0, s65, 0xffffff80
	s_nop 0
	global_load_lds_dwordx4 v150, s[42:43] offset:128
	s_waitcnt vmcnt(8)
	s_waitcnt lgkmcnt(0)
	s_barrier
	s_setprio 1
	s_waitcnt lgkmcnt(0)
	v_mfma_f32_16x16x32_bf16 v[60:63], v[128:131], v[190:193], v[60:63]
	v_mfma_f32_16x16x32_bf16 v[56:59], v[136:139], v[190:193], v[56:59]
	v_mfma_f32_16x16x32_bf16 v[52:55], v[128:131], v[198:201], v[52:55]
	v_mfma_f32_16x16x32_bf16 v[48:51], v[136:139], v[198:201], v[48:51]
	v_mfma_f32_16x16x32_bf16 v[36:39], v[128:131], v[206:209], v[36:39]
	v_mfma_f32_16x16x32_bf16 v[32:35], v[136:139], v[206:209], v[32:35]
	v_mfma_f32_16x16x32_bf16 v[20:23], v[128:131], v[214:217], v[20:23]
	v_mfma_f32_16x16x32_bf16 v[16:19], v[136:139], v[214:217], v[16:19]
	v_mfma_f32_16x16x32_bf16 v[60:63], v[132:135], v[194:197], v[60:63]
	v_mfma_f32_16x16x32_bf16 v[56:59], v[140:143], v[194:197], v[56:59]
	v_mfma_f32_16x16x32_bf16 v[52:55], v[132:135], v[202:205], v[52:55]
	v_mfma_f32_16x16x32_bf16 v[48:51], v[140:143], v[202:205], v[48:51]
	v_mfma_f32_16x16x32_bf16 v[36:39], v[132:135], v[210:213], v[36:39]
	v_mfma_f32_16x16x32_bf16 v[32:35], v[140:143], v[210:213], v[32:35]
	v_mfma_f32_16x16x32_bf16 v[20:23], v[132:135], v[218:221], v[20:23]
	v_mfma_f32_16x16x32_bf16 v[16:19], v[140:143], v[218:221], v[16:19]
	s_setprio 0
	s_setprio 1
	v_mfma_f32_16x16x32_bf16 v[44:47], v[168:171], v[190:193], v[44:47]
	v_mfma_f32_16x16x32_bf16 v[40:43], v[176:179], v[190:193], v[40:43]
	v_mfma_f32_16x16x32_bf16 v[28:31], v[168:171], v[198:201], v[28:31]
	v_mfma_f32_16x16x32_bf16 v[24:27], v[176:179], v[198:201], v[24:27]
	v_mfma_f32_16x16x32_bf16 v[12:15], v[168:171], v[206:209], v[12:15]
	v_mfma_f32_16x16x32_bf16 v[8:11], v[176:179], v[206:209], v[8:11]
	v_mfma_f32_16x16x32_bf16 v[4:7], v[168:171], v[214:217], v[4:7]
	v_mfma_f32_16x16x32_bf16 v[0:3], v[176:179], v[214:217], v[0:3]
	v_mfma_f32_16x16x32_bf16 v[44:47], v[172:175], v[194:197], v[44:47]
	v_mfma_f32_16x16x32_bf16 v[40:43], v[180:183], v[194:197], v[40:43]
	v_mfma_f32_16x16x32_bf16 v[28:31], v[172:175], v[202:205], v[28:31]
	v_mfma_f32_16x16x32_bf16 v[24:27], v[180:183], v[202:205], v[24:27]
	v_mfma_f32_16x16x32_bf16 v[12:15], v[172:175], v[210:213], v[12:15]
	v_mfma_f32_16x16x32_bf16 v[8:11], v[180:183], v[210:213], v[8:11]
	v_mfma_f32_16x16x32_bf16 v[4:7], v[172:175], v[218:221], v[4:7]
	v_mfma_f32_16x16x32_bf16 v[0:3], v[180:183], v[218:221], v[0:3]
	s_setprio 0
	s_barrier
	s_add_u32 s6, s6, 0x100
	s_addc_u32 s7, s7, 0
	s_add_u32 s8, s8, 0x100
	s_addc_u32 s66, s66, 0
	s_cmp_ge_u32 s90, s55
	s_mov_b32 s42, s90
	s_cbranch_scc0 .LBB0_246
	s_and_b64 vcc, exec, s[86:87]
	s_cbranch_vccz .LBB0_249
	s_barrier
